# phase-0 rmsnorm loop: loop-invariant norm_gain vectors loaded once before the loop (no per-step store-ack waits)
# speedup vs baseline: 1.0106x; 1.0011x over previous
; DI void phase0(const Params& p, unsigned char* smem) {
;     ...
;     const int lane = tid & 63, wave = tid >> 6;
;     bf16_t* xn = (bf16_t*)(p.ws + WS_XN);
;     for (int row = b * 4 + wave; row < T_; row += G * 8) {
;         const int row2 = row + G * 4;
;         const f32x4* xr = (const f32x4*)(p.x + (size_t)row * DM);
;         const f32x4* xr2 = (const f32x4*)(p.x + (size_t)row2 * DM);
;         f32x4 v[8], w[8]; float ss = 0.f, ss2 = 0.f;
; #pragma unroll
;         for (int i = 0; i < 8; ++i) { v[i] = xr[lane + 64 * i]; w[i] = xr2[lane + 64 * i]; }
; #pragma unroll
;         for (int i = 0; i < 8; ++i) {
;             ss += v[i].x * v[i].x + v[i].y * v[i].y + v[i].z * v[i].z + v[i].w * v[i].w;
;             ss2 += w[i].x * w[i].x + w[i].y * w[i].y + w[i].z * w[i].z + w[i].w * w[i].w;
;     ...
;             const f32x4 g = ((const f32x4*)p.norm_gain)[lane + 64 * i];
.LBB0_71:
	v_ashrrev_i32_e32 v3, 6, v2
	s_lshl_b32 s0, s38, 2
	v_add_u32_e32 v42, s0, v3
	v_writelane_b32 v246, s0, 0
	s_mov_b32 s0, 0x8000
	v_cmp_gt_i32_e32 vcc, s0, v42
	v_and_b32_e32 v142, 64, v236
	v_xor_b32_e32 v239, 1, v236
	v_xor_b32_e32 v238, 2, v236
	v_xor_b32_e32 v237, 4, v236
	v_xor_b32_e32 v143, 8, v236
	v_xor_b32_e32 v73, 16, v236
	v_xor_b32_e32 v1, 32, v236
	s_and_saveexec_b64 s[4:5], vcc
	s_cbranch_execz .LBB0_74
	v_add_u32_e32 v4, 64, v142
	v_cmp_lt_i32_e32 vcc, v239, v4
	v_and_b32_e32 v2, 63, v2
	v_lshlrev_b32_e32 v44, 4, v2
	v_cndmask_b32_e32 v5, v236, v239, vcc
	v_cmp_lt_i32_e32 vcc, v238, v4
	v_lshlrev_b32_e32 v75, 2, v5
	v_mov_b32_e32 v45, 0
	v_cndmask_b32_e32 v5, v236, v238, vcc
	v_cmp_lt_i32_e32 vcc, v237, v4
	v_lshlrev_b32_e32 v76, 2, v5
	s_movk_i32 s15, 0x1080
	v_cndmask_b32_e32 v5, v236, v237, vcc
	v_cmp_lt_i32_e32 vcc, v143, v4
	v_lshlrev_b32_e32 v77, 2, v5
	s_lshl_b32 s11, s33, 3
	v_cndmask_b32_e32 v5, v236, v143, vcc
	v_cmp_lt_i32_e32 vcc, v73, v4
	v_lshlrev_b32_e32 v78, 2, v5
	v_lshlrev_b32_e32 v56, 3, v2
	v_cndmask_b32_e32 v5, v236, v73, vcc
	v_cmp_lt_i32_e32 vcc, v1, v4
	v_lshlrev_b32_e32 v79, 2, v5
	v_mov_b32_e32 v5, v45
	v_cndmask_b32_e32 v4, v236, v1, vcc
	v_lshlrev_b32_e32 v80, 2, v4
	v_or_b32_e32 v4, 0x1000, v44
	s_waitcnt lgkmcnt(0)
	v_lshl_add_u64 v[48:49], s[44:45], 0, v[4:5]
	v_or_b32_e32 v4, 0x1400, v44
	v_lshl_add_u64 v[50:51], s[44:45], 0, v[4:5]
	v_or_b32_e32 v4, 0x1800, v44
	v_lshl_add_u64 v[52:53], s[44:45], 0, v[4:5]
	v_or_b32_e32 v4, 0x1c00, v44
	v_lshl_add_u64 v[54:55], s[44:45], 0, v[4:5]
	v_mov_b64_e32 v[4:5], s[72:73]
	v_mad_i64_i32 v[58:59], s[0:1], v42, s15, v[4:5]
	s_lshl_b32 s1, s78, 2
	s_lshl_b32 s0, s2, 3
	s_add_i32 s1, s1, s11
	s_add_i32 s1, s1, s0
	v_add_u32_e32 v2, s1, v3
	v_ashrrev_i32_e32 v3, 31, v2
	s_lshl_b32 s6, s33, 4
	v_ashrrev_i32_e32 v43, 31, v42
	v_lshlrev_b64 v[6:7], 13, v[2:3]
	s_ashr_i32 s7, s6, 31
	v_lshl_add_u64 v[60:61], s[40:41], 0, v[6:7]
	v_lshlrev_b64 v[6:7], 13, v[42:43]
	v_lshl_add_u64 v[46:47], s[44:45], 0, v[44:45]
	s_movk_i32 s3, 0x1000
	v_mov_b32_e32 v57, v45
	s_mul_i32 s16, s33, 0x10800
	s_mul_hi_i32 s17, s6, 0x1080
	s_lshl_b64 s[18:19], s[6:7], 13
	v_lshl_add_u64 v[62:63], s[40:41], 0, v[6:7]
	v_mad_i64_i32 v[64:65], s[0:1], v2, s15, v[4:5]
	s_mov_b64 s[20:21], 0
	s_mov_b32 s22, 0x3a000000
	v_mov_b32_e32 v66, 0x358637bd
	s_mov_b32 s7, 0x800000
	s_mov_b32 s11, 0x19dc5000
	s_movk_i32 s15, 0x7fff
	global_load_dwordx4 v[160:163], v[46:47], off
	global_load_dwordx4 v[164:167], v[46:47], off offset:1024
	global_load_dwordx4 v[168:171], v[46:47], off offset:2048
	global_load_dwordx4 v[172:175], v[46:47], off offset:3072
	global_load_dwordx4 v[176:179], v[48:49], off
	global_load_dwordx4 v[180:183], v[50:51], off
	global_load_dwordx4 v[184:187], v[52:53], off
	global_load_dwordx4 v[188:191], v[54:55], off
.LBB0_73:
	v_lshl_add_u64 v[2:3], v[62:63], 0, v[44:45]
	v_lshl_add_u64 v[6:7], v[60:61], 0, v[44:45]
	v_lshl_add_u64 v[4:5], v[58:59], 0, v[56:57]
	global_load_dwordx4 v[86:89], v[6:7], off
	global_load_dwordx4 v[90:93], v[2:3], off
	global_load_dwordx4 v[94:97], v[6:7], off offset:1024
	global_load_dwordx4 v[98:101], v[2:3], off offset:1024
	global_load_dwordx4 v[102:105], v[6:7], off offset:2048
	global_load_dwordx4 v[106:109], v[2:3], off offset:2048
	global_load_dwordx4 v[34:37], v[6:7], off offset:3072
	global_load_dwordx4 v[38:41], v[2:3], off offset:3072
	v_add_co_u32_e32 v14, vcc, s3, v2
	v_add_co_u32_e64 v68, s[0:1], s11, v4
	s_nop 0
	v_addc_co_u32_e32 v15, vcc, 0, v3, vcc
	v_lshl_add_u64 v[8:9], v[64:65], 0, v[56:57]
	v_addc_co_u32_e64 v69, s[0:1], 0, v5, s[0:1]
	v_add_co_u32_e32 v110, vcc, s3, v6
	global_load_dwordx4 v[26:29], v[14:15], off
	global_load_dwordx4 v[18:21], v[14:15], off offset:1024
	global_load_dwordx4 v[10:13], v[14:15], off offset:2048
	global_load_dwordx4 v[2:5], v[14:15], off offset:3072
	v_add_co_u32_e64 v70, s[0:1], s11, v8
	v_addc_co_u32_e32 v111, vcc, 0, v7, vcc
	s_nop 0
	v_addc_co_u32_e64 v71, s[0:1], 0, v9, s[0:1]
	global_load_dwordx4 v[30:33], v[110:111], off
	global_load_dwordx4 v[22:25], v[110:111], off offset:1024
	global_load_dwordx4 v[14:17], v[110:111], off offset:2048
	global_load_dwordx4 v[6:9], v[110:111], off offset:3072
	v_add_u32_e32 v42, s6, v42
	v_lshl_add_u64 v[58:59], v[58:59], 0, s[16:17]
	v_lshl_add_u64 v[60:61], v[60:61], 0, s[18:19]
	v_lshl_add_u64 v[62:63], v[62:63], 0, s[18:19]
	v_lshl_add_u64 v[64:65], v[64:65], 0, s[16:17]
	s_waitcnt vmcnt(15)
	v_mov_b32_e32 v112, v87
	s_waitcnt vmcnt(14)
	v_mov_b32_e32 v113, v91
	s_waitcnt vmcnt(13)
	v_mov_b32_e32 v116, v95
	s_waitcnt vmcnt(12)
	v_mov_b32_e32 v117, v99
	s_waitcnt vmcnt(11)
	v_mov_b32_e32 v120, v103
	s_waitcnt vmcnt(10)
	v_mov_b32_e32 v121, v107
	s_waitcnt vmcnt(9)
	v_mov_b32_e32 v124, v35
	s_waitcnt vmcnt(8)
	v_mov_b32_e32 v125, v39
	v_mov_b32_e32 v110, v86
	v_mov_b32_e32 v111, v90
	v_mov_b32_e32 v114, v94
	v_mov_b32_e32 v115, v98
	v_mov_b32_e32 v118, v102
	v_mov_b32_e32 v119, v106
	v_mov_b32_e32 v122, v34
	v_mov_b32_e32 v123, v38
	v_pk_mul_f32 v[112:113], v[112:113], v[112:113]
	v_pk_mul_f32 v[116:117], v[116:117], v[116:117]
	v_pk_mul_f32 v[120:121], v[120:121], v[120:121]
	v_pk_mul_f32 v[124:125], v[124:125], v[124:125]
	v_mov_b32_e32 v128, v96
	v_mov_b32_e32 v129, v100
	v_pk_fma_f32 v[110:111], v[110:111], v[110:111], v[112:113]
	v_pk_fma_f32 v[112:113], v[114:115], v[114:115], v[116:117]
	v_pk_fma_f32 v[114:115], v[118:119], v[118:119], v[120:121]
	v_pk_fma_f32 v[116:117], v[122:123], v[122:123], v[124:125]
	s_waitcnt vmcnt(7)
	v_mov_b32_e32 v120, v27
	s_waitcnt vmcnt(6)
	v_mov_b32_e32 v121, v19
	s_waitcnt vmcnt(5)
; DI void phase0(const Params& p, unsigned char* smem) {
;     ...
;         for (int i = 0; i < 8; ++i) {
;             ss += v[i].x * v[i].x + v[i].y * v[i].y + v[i].z * v[i].z + v[i].w * v[i].w;
;             ss2 += w[i].x * w[i].x + w[i].y * w[i].y + w[i].z * w[i].z + w[i].w * w[i].w;
;         }
;         ss = wave_sum(ss); ss2 = wave_sum(ss2);
	v_mov_b32_e32 v124, v11
	s_waitcnt vmcnt(4)
	v_mov_b32_e32 v125, v3
	v_mov_b32_e32 v126, v88
	v_mov_b32_e32 v127, v92
	v_mov_b32_e32 v132, v36
	v_mov_b32_e32 v133, v40
	v_mov_b32_e32 v118, v26
	v_mov_b32_e32 v119, v18
	v_mov_b32_e32 v122, v10
	v_mov_b32_e32 v123, v2
	v_pk_fma_f32 v[112:113], v[128:129], v[128:129], v[112:113]
	v_pk_mul_f32 v[120:121], v[120:121], v[120:121]
	v_pk_mul_f32 v[124:125], v[124:125], v[124:125]
	s_waitcnt vmcnt(3)
	v_mov_b32_e32 v128, v31
	s_waitcnt vmcnt(2)
	v_mov_b32_e32 v129, v23
	v_mov_b32_e32 v130, v104
	v_mov_b32_e32 v131, v108
	v_mov_b32_e32 v134, v89
	v_mov_b32_e32 v135, v93
	v_mov_b32_e32 v136, v97
	v_mov_b32_e32 v137, v101
	v_pk_fma_f32 v[110:111], v[126:127], v[126:127], v[110:111]
	v_pk_fma_f32 v[116:117], v[132:133], v[132:133], v[116:117]
	v_mov_b32_e32 v126, v30
	v_mov_b32_e32 v127, v22
	s_waitcnt vmcnt(1)
	v_mov_b32_e32 v132, v15
	s_waitcnt vmcnt(0)
	v_mov_b32_e32 v133, v7
	v_pk_fma_f32 v[118:119], v[118:119], v[118:119], v[120:121]
	v_pk_fma_f32 v[120:121], v[122:123], v[122:123], v[124:125]
	v_pk_mul_f32 v[122:123], v[128:129], v[128:129]
	v_mov_b32_e32 v138, v105
	v_mov_b32_e32 v139, v109
	v_mov_b32_e32 v144, v28
	v_mov_b32_e32 v145, v20
	v_mov_b32_e32 v146, v12
	v_mov_b32_e32 v147, v4
	v_pk_fma_f32 v[114:115], v[130:131], v[130:131], v[114:115]
	v_mov_b32_e32 v130, v14
	v_mov_b32_e32 v131, v6
	v_mov_b32_e32 v152, v32
	v_mov_b32_e32 v153, v24
	v_pk_fma_f32 v[110:111], v[134:135], v[134:135], v[110:111]
	v_pk_fma_f32 v[112:113], v[136:137], v[136:137], v[112:113]
	v_pk_mul_f32 v[124:125], v[132:133], v[132:133]
	v_pk_fma_f32 v[122:123], v[126:127], v[126:127], v[122:123]
	v_mov_b32_e32 v140, v37
	v_mov_b32_e32 v141, v41
	v_mov_b32_e32 v148, v29
	v_mov_b32_e32 v149, v21
	v_mov_b32_e32 v154, v16
	v_mov_b32_e32 v155, v8
	v_mov_b32_e32 v156, v33
	v_mov_b32_e32 v157, v25
	v_pk_fma_f32 v[114:115], v[138:139], v[138:139], v[114:115]
	v_pk_fma_f32 v[118:119], v[144:145], v[144:145], v[118:119]
	v_pk_add_f32 v[110:111], v[110:111], v[112:113]
	v_pk_fma_f32 v[112:113], v[146:147], v[146:147], v[120:121]
	v_pk_fma_f32 v[120:121], v[130:131], v[130:131], v[124:125]
	v_pk_fma_f32 v[122:123], v[152:153], v[152:153], v[122:123]
	v_pk_fma_f32 v[116:117], v[140:141], v[140:141], v[116:117]
	v_pk_fma_f32 v[118:119], v[148:149], v[148:149], v[118:119]
	v_pk_add_f32 v[110:111], v[110:111], v[114:115]
	v_pk_fma_f32 v[114:115], v[154:155], v[154:155], v[120:121]
	v_pk_fma_f32 v[120:121], v[156:157], v[156:157], v[122:123]
	v_mov_b32_e32 v150, v13
	v_mov_b32_e32 v151, v5
	v_mov_b32_e32 v158, v17
	v_mov_b32_e32 v159, v9
	v_pk_add_f32 v[110:111], v[110:111], v[116:117]
	v_mov_b32_e32 v117, v118
	v_mov_b32_e32 v116, v120
	v_pk_fma_f32 v[112:113], v[150:151], v[150:151], v[112:113]
	v_pk_fma_f32 v[114:115], v[158:159], v[158:159], v[114:115]
	v_mov_b32_e32 v118, v121
	v_pk_add_f32 v[110:111], v[110:111], v[116:117]
	v_mov_b32_e32 v123, v112
	v_mov_b32_e32 v122, v114
	v_pk_add_f32 v[110:111], v[110:111], v[118:119]
	v_mov_b32_e32 v112, v115
	v_pk_add_f32 v[110:111], v[110:111], v[122:123]
	s_nop 0
	v_pk_add_f32 v[110:111], v[110:111], v[112:113]
	ds_bpermute_b32 v113, v75, v111
	ds_bpermute_b32 v112, v75, v110
	s_waitcnt lgkmcnt(0)
	v_pk_add_f32 v[110:111], v[110:111], v[112:113]
	ds_bpermute_b32 v113, v76, v111
	ds_bpermute_b32 v112, v76, v110
	s_waitcnt lgkmcnt(0)
	v_pk_add_f32 v[110:111], v[110:111], v[112:113]
	ds_bpermute_b32 v113, v77, v111
	ds_bpermute_b32 v112, v77, v110
	s_waitcnt lgkmcnt(0)
	v_pk_add_f32 v[110:111], v[110:111], v[112:113]
	ds_bpermute_b32 v113, v78, v111
	ds_bpermute_b32 v112, v78, v110
	s_waitcnt lgkmcnt(0)
	v_pk_add_f32 v[110:111], v[110:111], v[112:113]
	ds_bpermute_b32 v113, v79, v111
	ds_bpermute_b32 v112, v79, v110
	s_waitcnt lgkmcnt(0)
	v_pk_add_f32 v[110:111], v[110:111], v[112:113]
	ds_bpermute_b32 v113, v80, v111
	ds_bpermute_b32 v112, v80, v110
	s_waitcnt lgkmcnt(0)
; DI unsigned pk2(float a, float b) { f2_t v = {a, b}; bf2_t r = __builtin_convertvector(v, bf2_t); return __builtin_bit_cast(unsigned, r); }
; DI void phase0(const Params& p, unsigned char* smem) {
;     ...
;         const float rs = rsqrtf(ss * (1.f / DM) + EPS), rs2 = rsqrtf(ss2 * (1.f / DM) + EPS);
; #pragma unroll
;         for (int i = 0; i < 8; ++i) {
;             const f32x4 g = ((const f32x4*)p.norm_gain)[lane + 64 * i];
;             u32x2 o; o.x = pk2(v[i].x * rs * g.x, v[i].y * rs * g.y); o.y = pk2(v[i].z * rs * g.z, v[i].w * rs * g.w);
;             *(u32x2*)(xn + (size_t)row * LDK + (lane + 64 * i) * 4) = o;
;             u32x2 o2; o2.x = pk2(w[i].x * rs2 * g.x, w[i].y * rs2 * g.y); o2.y = pk2(w[i].z * rs2 * g.z, w[i].w * rs2 * g.w);
;             *(u32x2*)(xn + (size_t)row2 * LDK + (lane + 64 * i) * 4) = o2;
	v_pk_add_f32 v[110:111], v[110:111], v[112:113]
	s_nop 0
	v_pk_fma_f32 v[110:111], v[110:111], s[22:23], v[66:67] op_sel_hi:[1,0,0]
	s_nop 0
	v_mul_f32_e32 v72, 0x4b800000, v111
	v_cmp_gt_f32_e64 s[0:1], s7, v111
	v_mul_f32_e32 v43, 0x4b800000, v110
	v_cmp_gt_f32_e32 vcc, s7, v110
	v_cndmask_b32_e64 v72, v111, v72, s[0:1]
	v_rsq_f32_e32 v72, v72
	v_cndmask_b32_e32 v43, v110, v43, vcc
	v_rsq_f32_e32 v43, v43
	v_mul_f32_e32 v74, 0x45800000, v72
	v_cndmask_b32_e64 v74, v72, v74, s[0:1]
	v_mul_f32_e32 v81, 0x45800000, v43
	v_cndmask_b32_e32 v72, v43, v81, vcc
	v_pk_mul_f32 v[90:91], v[90:91], v[74:75] op_sel_hi:[1,0]
	v_pk_mul_f32 v[92:93], v[92:93], v[74:75] op_sel_hi:[1,0]
	v_pk_mul_f32 v[86:87], v[86:87], v[72:73] op_sel_hi:[1,0]
	v_pk_mul_f32 v[88:89], v[88:89], v[72:73] op_sel_hi:[1,0]
	v_pk_mul_f32 v[90:91], v[160:161], v[90:91]
	v_pk_mul_f32 v[92:93], v[162:163], v[92:93]
	v_pk_mul_f32 v[82:83], v[160:161], v[86:87]
	v_pk_mul_f32 v[84:85], v[162:163], v[88:89]
	v_cvt_pk_bf16_f32 v86, v90, v91
	v_cvt_pk_bf16_f32 v87, v92, v93
	v_cvt_pk_bf16_f32 v82, v82, v83
	v_cvt_pk_bf16_f32 v83, v84, v85
	global_store_dwordx2 v[68:69], v[86:87], off
	global_store_dwordx2 v[70:71], v[82:83], off
	v_pk_mul_f32 v[86:87], v[98:99], v[74:75] op_sel_hi:[1,0]
	v_pk_mul_f32 v[88:89], v[100:101], v[74:75] op_sel_hi:[1,0]
	v_pk_mul_f32 v[90:91], v[94:95], v[72:73] op_sel_hi:[1,0]
	v_pk_mul_f32 v[92:93], v[96:97], v[72:73] op_sel_hi:[1,0]
	v_pk_mul_f32 v[38:39], v[38:39], v[74:75] op_sel_hi:[1,0]
	v_pk_mul_f32 v[40:41], v[40:41], v[74:75] op_sel_hi:[1,0]
	v_pk_mul_f32 v[34:35], v[34:35], v[72:73] op_sel_hi:[1,0]
	v_pk_mul_f32 v[36:37], v[36:37], v[72:73] op_sel_hi:[1,0]
	v_pk_mul_f32 v[26:27], v[26:27], v[74:75] op_sel_hi:[1,0]
	v_pk_mul_f32 v[28:29], v[28:29], v[74:75] op_sel_hi:[1,0]
	v_pk_mul_f32 v[30:31], v[30:31], v[72:73] op_sel_hi:[1,0]
	v_pk_mul_f32 v[32:33], v[32:33], v[72:73] op_sel_hi:[1,0]
	v_pk_mul_f32 v[18:19], v[18:19], v[74:75] op_sel_hi:[1,0]
	v_pk_mul_f32 v[20:21], v[20:21], v[74:75] op_sel_hi:[1,0]
	v_pk_mul_f32 v[22:23], v[22:23], v[72:73] op_sel_hi:[1,0]
	v_pk_mul_f32 v[24:25], v[24:25], v[72:73] op_sel_hi:[1,0]
	v_pk_mul_f32 v[10:11], v[10:11], v[74:75] op_sel_hi:[1,0]
	v_pk_mul_f32 v[12:13], v[12:13], v[74:75] op_sel_hi:[1,0]
	v_pk_mul_f32 v[14:15], v[14:15], v[72:73] op_sel_hi:[1,0]
	v_pk_mul_f32 v[16:17], v[16:17], v[72:73] op_sel_hi:[1,0]
	v_pk_mul_f32 v[2:3], v[2:3], v[74:75] op_sel_hi:[1,0]
	v_pk_mul_f32 v[4:5], v[4:5], v[74:75] op_sel_hi:[1,0]
	v_cmp_lt_i32_e32 vcc, s15, v42
	v_pk_mul_f32 v[6:7], v[6:7], v[72:73] op_sel_hi:[1,0]
	v_pk_mul_f32 v[8:9], v[8:9], v[72:73] op_sel_hi:[1,0]
	s_or_b64 s[20:21], vcc, s[20:21]
	v_pk_mul_f32 v[86:87], v[164:165], v[86:87]
	v_pk_mul_f32 v[88:89], v[166:167], v[88:89]
	v_pk_mul_f32 v[82:83], v[164:165], v[90:91]
	v_pk_mul_f32 v[84:85], v[166:167], v[92:93]
	v_cvt_pk_bf16_f32 v86, v86, v87
	v_cvt_pk_bf16_f32 v87, v88, v89
	v_cvt_pk_bf16_f32 v82, v82, v83
	v_cvt_pk_bf16_f32 v83, v84, v85
	global_store_dwordx2 v[68:69], v[86:87], off offset:512
	global_store_dwordx2 v[70:71], v[82:83], off offset:512
	v_pk_mul_f32 v[86:87], v[106:107], v[74:75] op_sel_hi:[1,0]
	v_pk_mul_f32 v[88:89], v[108:109], v[74:75] op_sel_hi:[1,0]
	v_pk_mul_f32 v[90:91], v[102:103], v[72:73] op_sel_hi:[1,0]
	v_pk_mul_f32 v[92:93], v[104:105], v[72:73] op_sel_hi:[1,0]
	v_pk_mul_f32 v[86:87], v[86:87], v[168:169]
	v_pk_mul_f32 v[88:89], v[88:89], v[170:171]
	v_pk_mul_f32 v[82:83], v[168:169], v[90:91]
	v_pk_mul_f32 v[84:85], v[170:171], v[92:93]
	v_cvt_pk_bf16_f32 v86, v86, v87
	v_cvt_pk_bf16_f32 v87, v88, v89
	v_cvt_pk_bf16_f32 v82, v82, v83
	v_cvt_pk_bf16_f32 v83, v84, v85
	global_store_dwordx2 v[68:69], v[86:87], off offset:1024
	global_store_dwordx2 v[70:71], v[82:83], off offset:1024
	v_pk_mul_f32 v[38:39], v[38:39], v[172:173]
	v_pk_mul_f32 v[40:41], v[40:41], v[174:175]
	v_pk_mul_f32 v[34:35], v[34:35], v[172:173]
	v_pk_mul_f32 v[36:37], v[36:37], v[174:175]
	v_cvt_pk_bf16_f32 v38, v38, v39
	v_cvt_pk_bf16_f32 v39, v40, v41
	v_cvt_pk_bf16_f32 v34, v34, v35
	v_cvt_pk_bf16_f32 v35, v36, v37
	global_store_dwordx2 v[68:69], v[38:39], off offset:1536
	global_store_dwordx2 v[70:71], v[34:35], off offset:1536
	v_pk_mul_f32 v[26:27], v[26:27], v[176:177]
	v_pk_mul_f32 v[28:29], v[28:29], v[178:179]
	v_pk_mul_f32 v[30:31], v[30:31], v[176:177]
	v_pk_mul_f32 v[32:33], v[32:33], v[178:179]
	v_cvt_pk_bf16_f32 v26, v26, v27
	v_cvt_pk_bf16_f32 v27, v28, v29
	v_cvt_pk_bf16_f32 v28, v30, v31
	v_cvt_pk_bf16_f32 v29, v32, v33
	global_store_dwordx2 v[68:69], v[26:27], off offset:2048
	global_store_dwordx2 v[70:71], v[28:29], off offset:2048
	v_pk_mul_f32 v[18:19], v[18:19], v[180:181]
	v_pk_mul_f32 v[20:21], v[20:21], v[182:183]
	v_pk_mul_f32 v[22:23], v[22:23], v[180:181]
	v_pk_mul_f32 v[24:25], v[24:25], v[182:183]
	v_cvt_pk_bf16_f32 v18, v18, v19
	v_cvt_pk_bf16_f32 v19, v20, v21
	v_cvt_pk_bf16_f32 v20, v22, v23
	v_cvt_pk_bf16_f32 v21, v24, v25
	global_store_dwordx2 v[68:69], v[18:19], off offset:2560
	global_store_dwordx2 v[70:71], v[20:21], off offset:2560
	v_pk_mul_f32 v[10:11], v[10:11], v[184:185]
	v_pk_mul_f32 v[12:13], v[12:13], v[186:187]
	v_pk_mul_f32 v[14:15], v[14:15], v[184:185]
	v_pk_mul_f32 v[16:17], v[16:17], v[186:187]
	v_cvt_pk_bf16_f32 v10, v10, v11
	v_cvt_pk_bf16_f32 v11, v12, v13
	v_cvt_pk_bf16_f32 v12, v14, v15
	v_cvt_pk_bf16_f32 v13, v16, v17
	global_store_dwordx2 v[68:69], v[10:11], off offset:3072
	global_store_dwordx2 v[70:71], v[12:13], off offset:3072
	v_pk_mul_f32 v[2:3], v[2:3], v[188:189]
	v_pk_mul_f32 v[4:5], v[4:5], v[190:191]
	v_pk_mul_f32 v[6:7], v[6:7], v[188:189]
	v_pk_mul_f32 v[8:9], v[8:9], v[190:191]
	v_cvt_pk_bf16_f32 v2, v2, v3
	v_cvt_pk_bf16_f32 v3, v4, v5
	v_cvt_pk_bf16_f32 v4, v6, v7
	v_cvt_pk_bf16_f32 v5, v8, v9
	global_store_dwordx2 v[68:69], v[2:3], off offset:3584
	global_store_dwordx2 v[70:71], v[4:5], off offset:3584
	s_andn2_b64 exec, exec, s[20:21]
	s_cbranch_execnz .LBB0_73
